# pool-fold items: the LDS staging wait overlaps the first step's per-lane loads
# baseline (speedup 1.0000x reference)
; __global__ void __launch_bounds__(NWAVES * 64, 2) fwd(Args a) {
;     ...
;                 const float* wp = a.in[I_WPOOL] + (size_t)(g * 128 + 8 * cb) * 128;
; #pragma unroll 8
;                 for (int d = 0; d < 128; ++d) {
;                     const float wo = a.in[I_WOUT][(size_t)(ATTW + g * 128 + d) * D + n] * a.in[I_PSCALE][g * 128 + d];
.LBB0_80:
	s_movk_i32 s0, 0xb000
	v_add_co_u32_e64 v42, s[0:1], s0, v14
	v_add_co_u32_e32 v24, vcc, 0xffff9000, v14
	s_nop 0
	v_addc_co_u32_e64 v43, s[0:1], -1, v15, s[0:1]
	s_movk_i32 s0, 0xd000
	s_nop 0
	v_add_co_u32_e64 v44, s[0:1], s0, v14
	s_add_u32 s10, s6, s8
	s_nop 0
	v_addc_co_u32_e64 v45, s[0:1], -1, v15, s[0:1]
	s_movk_i32 s0, 0xe000
	s_nop 0
	v_add_co_u32_e64 v46, s[0:1], s0, v14
	s_addc_u32 s11, s40, s9
	s_nop 0
	v_addc_co_u32_e64 v47, s[0:1], -1, v15, s[0:1]
	v_addc_co_u32_e32 v25, vcc, -1, v15, vcc
	global_load_dword v41, v[14:15], off offset:-4096
	global_load_dword v115, v[14:15], off
	global_load_dword v2, v[42:43], off offset:-4096
	global_load_dword v114, v[42:43], off
	global_load_dword v116, v[44:45], off offset:-4096
	global_load_dword v117, v[44:45], off
	global_load_dword v118, v[46:47], off
	s_nop 0
	global_load_dwordx4 v[42:45], v3, s[10:11]
	global_load_dwordx4 v[46:49], v3, s[10:11] offset:16
	s_mov_b64 s[0:1], 0x8000
	global_load_dword v25, v[24:25], off
	v_lshl_add_u64 v[14:15], v[14:15], 0, s[0:1]
	s_add_u32 s0, s41, s8
	s_addc_u32 s1, s42, s9
	s_add_u32 s8, s8, 32
	s_addc_u32 s9, s9, 0
	s_cmpk_eq_i32 s8, 0x200
	v_add_u32_e32 v222, s78, v223
	s_waitcnt vmcnt(10)
	ds_write_b128 v222, v[224:227]
	ds_write_b128 v222, v[228:231] offset:1024
	ds_write_b128 v222, v[232:235] offset:2048
	ds_write_b128 v222, v[236:239] offset:3072
	v_mov_b32_e32 v222, s78
	s_waitcnt lgkmcnt(0)
